# final RMSNorm unrolled and double-buffered: gain vector loaded once, next row's loads in flight while the current row is normalised and stored (counted vmcnt waits)
# speedup vs baseline: 1.0087x; 1.0087x over previous
.LBB0_2312:
	global_load_dwordx4 v[44:47], v[0:1], off
	global_load_dwordx4 v[48:51], v[0:1], off offset:1024
	global_load_dwordx4 v[52:55], v[0:1], off offset:2048
	global_load_dwordx4 v[56:59], v[0:1], off offset:3072
	v_lshl_add_u64 v[84:85], s[40:41], 0, v[4:5]
	global_load_dwordx4 v[60:63], v[84:85], off
	v_lshl_add_u64 v[86:87], s[40:41], 0, v[2:3]
	v_add_co_u32_e32 v86, vcc, 0x6600000, v86
	s_nop 1
	v_addc_co_u32_e32 v87, vcc, 0, v87, vcc
	global_load_dwordx2 v[64:65], v[86:87], off
	global_load_dwordx2 v[66:67], v[86:87], off offset:512
	global_load_dwordx2 v[68:69], v[86:87], off offset:1024
	global_load_dwordx2 v[70:71], v[86:87], off offset:1536
	v_lshl_add_u64 v[2:3], v[2:3], 0, s[0:1]
	v_lshl_add_u64 v[4:5], v[4:5], 0, s[2:3]
	v_lshl_add_u64 v[84:85], s[40:41], 0, v[4:5]
	global_load_dwordx4 v[72:75], v[84:85], off
	v_lshl_add_u64 v[86:87], s[40:41], 0, v[2:3]
	v_add_co_u32_e32 v86, vcc, 0x6600000, v86
	s_nop 1
	v_addc_co_u32_e32 v87, vcc, 0, v87, vcc
	global_load_dwordx2 v[76:77], v[86:87], off
	global_load_dwordx2 v[78:79], v[86:87], off offset:512
	global_load_dwordx2 v[80:81], v[86:87], off offset:1024
	global_load_dwordx2 v[82:83], v[86:87], off offset:1536
	v_lshl_add_u64 v[2:3], v[2:3], 0, s[0:1]
	v_lshl_add_u64 v[4:5], v[4:5], 0, s[2:3]
	s_waitcnt vmcnt(5)
	v_add_f32_e32 v42, v61, v60
	v_add_f32_e32 v43, v62, v63
	v_add_f32_e32 v42, v42, v43
	v_lshlrev_b32_e32 v26, 16, v64
	v_and_b32_e32 v27, 0xffff0000, v64
	v_add_f32_dpp v42, v42, v42 quad_perm:[1,0,3,2] row_mask:0xf bank_mask:0xf bound_ctrl:1
	v_lshlrev_b32_e32 v28, 16, v65
	v_and_b32_e32 v29, 0xffff0000, v65
	v_add_f32_dpp v42, v42, v42 quad_perm:[2,3,0,1] row_mask:0xf bank_mask:0xf bound_ctrl:1
	v_fmamk_f32 v42, v42, 0x3a800000, v9
	v_mul_f32_e32 v43, 0x4b800000, v42
	v_cmp_gt_f32_e32 vcc, s8, v42
	v_lshlrev_b32_e32 v30, 16, v66
	v_and_b32_e32 v31, 0xffff0000, v66
	v_cndmask_b32_e32 v42, v42, v43, vcc
	v_rsq_f32_e32 v42, v42
	v_lshlrev_b32_e32 v32, 16, v67
	v_and_b32_e32 v33, 0xffff0000, v67
	v_lshlrev_b32_e32 v34, 16, v68
	v_and_b32_e32 v35, 0xffff0000, v68
	v_mul_f32_e32 v43, 0x45800000, v42
	s_nop 0
	v_cndmask_b32_e32 v42, v42, v43, vcc
	v_lshlrev_b32_e32 v36, 16, v69
	v_and_b32_e32 v37, 0xffff0000, v69
	v_lshlrev_b32_e32 v38, 16, v70
	v_and_b32_e32 v39, 0xffff0000, v70
	v_lshlrev_b32_e32 v40, 16, v71
	v_and_b32_e32 v41, 0xffff0000, v71
	v_pk_mul_f32 v[26:27], v[42:43], v[26:27] op_sel_hi:[0,1]
	v_pk_mul_f32 v[28:29], v[42:43], v[28:29] op_sel_hi:[0,1]
	v_pk_mul_f32 v[30:31], v[42:43], v[30:31] op_sel_hi:[0,1]
	v_pk_mul_f32 v[32:33], v[42:43], v[32:33] op_sel_hi:[0,1]
	v_pk_mul_f32 v[34:35], v[42:43], v[34:35] op_sel_hi:[0,1]
	v_pk_mul_f32 v[36:37], v[42:43], v[36:37] op_sel_hi:[0,1]
	v_pk_mul_f32 v[38:39], v[42:43], v[38:39] op_sel_hi:[0,1]
	v_pk_mul_f32 v[40:41], v[42:43], v[40:41] op_sel_hi:[0,1]
	v_pk_mul_f32 v[10:11], v[44:45], v[26:27]
	v_pk_mul_f32 v[12:13], v[46:47], v[28:29]
	v_pk_mul_f32 v[14:15], v[48:49], v[30:31]
	v_pk_mul_f32 v[16:17], v[50:51], v[32:33]
	v_pk_mul_f32 v[18:19], v[52:53], v[34:35]
	v_pk_mul_f32 v[20:21], v[54:55], v[36:37]
	v_pk_mul_f32 v[22:23], v[56:57], v[38:39]
	v_pk_mul_f32 v[24:25], v[58:59], v[40:41]
	global_store_dwordx4 v[6:7], v[10:13], off offset:-3072
	global_store_dwordx4 v[6:7], v[14:17], off offset:-2048
	global_store_dwordx4 v[6:7], v[18:21], off offset:-1024
	global_store_dwordx4 v[6:7], v[22:25], off
	v_lshl_add_u64 v[6:7], v[6:7], 0, s[4:5]
	v_lshl_add_u64 v[2:3], v[2:3], 0, s[16:17]
	v_lshl_add_u64 v[4:5], v[4:5], 0, s[18:19]
	v_lshl_add_u64 v[84:85], s[40:41], 0, v[4:5]
	global_load_dwordx4 v[60:63], v[84:85], off
	v_lshl_add_u64 v[86:87], s[40:41], 0, v[2:3]
	v_add_co_u32_e32 v86, vcc, 0x6600000, v86
	s_nop 1
	v_addc_co_u32_e32 v87, vcc, 0, v87, vcc
	global_load_dwordx2 v[64:65], v[86:87], off
	global_load_dwordx2 v[66:67], v[86:87], off offset:512
	global_load_dwordx2 v[68:69], v[86:87], off offset:1024
	global_load_dwordx2 v[70:71], v[86:87], off offset:1536
	v_lshl_add_u64 v[2:3], v[2:3], 0, s[0:1]
	v_lshl_add_u64 v[4:5], v[4:5], 0, s[2:3]
	s_waitcnt vmcnt(9)
	v_add_f32_e32 v42, v73, v72
	v_add_f32_e32 v43, v74, v75
	v_add_f32_e32 v42, v42, v43
	v_lshlrev_b32_e32 v26, 16, v76
	v_and_b32_e32 v27, 0xffff0000, v76
	v_add_f32_dpp v42, v42, v42 quad_perm:[1,0,3,2] row_mask:0xf bank_mask:0xf bound_ctrl:1
	v_lshlrev_b32_e32 v28, 16, v77
	v_and_b32_e32 v29, 0xffff0000, v77
	v_add_f32_dpp v42, v42, v42 quad_perm:[2,3,0,1] row_mask:0xf bank_mask:0xf bound_ctrl:1
	v_fmamk_f32 v42, v42, 0x3a800000, v9
	v_mul_f32_e32 v43, 0x4b800000, v42
	v_cmp_gt_f32_e32 vcc, s8, v42
	v_lshlrev_b32_e32 v30, 16, v78
	v_and_b32_e32 v31, 0xffff0000, v78
	v_cndmask_b32_e32 v42, v42, v43, vcc
	v_rsq_f32_e32 v42, v42
	v_lshlrev_b32_e32 v32, 16, v79
	v_and_b32_e32 v33, 0xffff0000, v79
	v_lshlrev_b32_e32 v34, 16, v80
	v_and_b32_e32 v35, 0xffff0000, v80
	v_mul_f32_e32 v43, 0x45800000, v42
	s_nop 0
	v_cndmask_b32_e32 v42, v42, v43, vcc
	v_lshlrev_b32_e32 v36, 16, v81
	v_and_b32_e32 v37, 0xffff0000, v81
	v_lshlrev_b32_e32 v38, 16, v82
	v_and_b32_e32 v39, 0xffff0000, v82
	v_lshlrev_b32_e32 v40, 16, v83
	v_and_b32_e32 v41, 0xffff0000, v83
	v_pk_mul_f32 v[26:27], v[42:43], v[26:27] op_sel_hi:[0,1]
	v_pk_mul_f32 v[28:29], v[42:43], v[28:29] op_sel_hi:[0,1]
	v_pk_mul_f32 v[30:31], v[42:43], v[30:31] op_sel_hi:[0,1]
	v_pk_mul_f32 v[32:33], v[42:43], v[32:33] op_sel_hi:[0,1]
	v_pk_mul_f32 v[34:35], v[42:43], v[34:35] op_sel_hi:[0,1]
	v_pk_mul_f32 v[36:37], v[42:43], v[36:37] op_sel_hi:[0,1]
	v_pk_mul_f32 v[38:39], v[42:43], v[38:39] op_sel_hi:[0,1]
	v_pk_mul_f32 v[40:41], v[42:43], v[40:41] op_sel_hi:[0,1]
	v_pk_mul_f32 v[10:11], v[44:45], v[26:27]
	v_pk_mul_f32 v[12:13], v[46:47], v[28:29]
	v_pk_mul_f32 v[14:15], v[48:49], v[30:31]
	v_pk_mul_f32 v[16:17], v[50:51], v[32:33]
	v_pk_mul_f32 v[18:19], v[52:53], v[34:35]
	v_pk_mul_f32 v[20:21], v[54:55], v[36:37]
	v_pk_mul_f32 v[22:23], v[56:57], v[38:39]
	v_pk_mul_f32 v[24:25], v[58:59], v[40:41]
	global_store_dwordx4 v[6:7], v[10:13], off offset:-3072
	global_store_dwordx4 v[6:7], v[14:17], off offset:-2048
	global_store_dwordx4 v[6:7], v[18:21], off offset:-1024
	global_store_dwordx4 v[6:7], v[22:25], off
	v_lshl_add_u64 v[6:7], v[6:7], 0, s[4:5]
	v_lshl_add_u64 v[6:7], v[6:7], 0, s[20:21]
	v_lshl_add_u64 v[84:85], s[40:41], 0, v[4:5]
	global_load_dwordx4 v[72:75], v[84:85], off
	v_lshl_add_u64 v[86:87], s[40:41], 0, v[2:3]
	v_add_co_u32_e32 v86, vcc, 0x6600000, v86
	s_nop 1
	v_addc_co_u32_e32 v87, vcc, 0, v87, vcc
	global_load_dwordx2 v[76:77], v[86:87], off
	global_load_dwordx2 v[78:79], v[86:87], off offset:512
	global_load_dwordx2 v[80:81], v[86:87], off offset:1024
	global_load_dwordx2 v[82:83], v[86:87], off offset:1536
	v_lshl_add_u64 v[2:3], v[2:3], 0, s[0:1]
	v_lshl_add_u64 v[4:5], v[4:5], 0, s[2:3]
	s_waitcnt vmcnt(9)
	v_add_f32_e32 v42, v61, v60
	v_add_f32_e32 v43, v62, v63
	v_add_f32_e32 v42, v42, v43
	v_lshlrev_b32_e32 v26, 16, v64
	v_and_b32_e32 v27, 0xffff0000, v64
	v_add_f32_dpp v42, v42, v42 quad_perm:[1,0,3,2] row_mask:0xf bank_mask:0xf bound_ctrl:1
	v_lshlrev_b32_e32 v28, 16, v65
	v_and_b32_e32 v29, 0xffff0000, v65
	v_add_f32_dpp v42, v42, v42 quad_perm:[2,3,0,1] row_mask:0xf bank_mask:0xf bound_ctrl:1
	v_fmamk_f32 v42, v42, 0x3a800000, v9
	v_mul_f32_e32 v43, 0x4b800000, v42
	v_cmp_gt_f32_e32 vcc, s8, v42
	v_lshlrev_b32_e32 v30, 16, v66
	v_and_b32_e32 v31, 0xffff0000, v66
	v_cndmask_b32_e32 v42, v42, v43, vcc
	v_rsq_f32_e32 v42, v42
	v_lshlrev_b32_e32 v32, 16, v67
	v_and_b32_e32 v33, 0xffff0000, v67
	v_lshlrev_b32_e32 v34, 16, v68
	v_and_b32_e32 v35, 0xffff0000, v68
	v_mul_f32_e32 v43, 0x45800000, v42
	s_nop 0
	v_cndmask_b32_e32 v42, v42, v43, vcc
	v_lshlrev_b32_e32 v36, 16, v69
	v_and_b32_e32 v37, 0xffff0000, v69
	v_lshlrev_b32_e32 v38, 16, v70
	v_and_b32_e32 v39, 0xffff0000, v70
	v_lshlrev_b32_e32 v40, 16, v71
	v_and_b32_e32 v41, 0xffff0000, v71
	v_pk_mul_f32 v[26:27], v[42:43], v[26:27] op_sel_hi:[0,1]
	v_pk_mul_f32 v[28:29], v[42:43], v[28:29] op_sel_hi:[0,1]
	v_pk_mul_f32 v[30:31], v[42:43], v[30:31] op_sel_hi:[0,1]
	v_pk_mul_f32 v[32:33], v[42:43], v[32:33] op_sel_hi:[0,1]
	v_pk_mul_f32 v[34:35], v[42:43], v[34:35] op_sel_hi:[0,1]
	v_pk_mul_f32 v[36:37], v[42:43], v[36:37] op_sel_hi:[0,1]
	v_pk_mul_f32 v[38:39], v[42:43], v[38:39] op_sel_hi:[0,1]
	v_pk_mul_f32 v[40:41], v[42:43], v[40:41] op_sel_hi:[0,1]
	v_pk_mul_f32 v[10:11], v[44:45], v[26:27]
	v_pk_mul_f32 v[12:13], v[46:47], v[28:29]
	v_pk_mul_f32 v[14:15], v[48:49], v[30:31]
	v_pk_mul_f32 v[16:17], v[50:51], v[32:33]
	v_pk_mul_f32 v[18:19], v[52:53], v[34:35]
	v_pk_mul_f32 v[20:21], v[54:55], v[36:37]
	v_pk_mul_f32 v[22:23], v[56:57], v[38:39]
	v_pk_mul_f32 v[24:25], v[58:59], v[40:41]
	global_store_dwordx4 v[6:7], v[10:13], off offset:-3072
	global_store_dwordx4 v[6:7], v[14:17], off offset:-2048
	global_store_dwordx4 v[6:7], v[18:21], off offset:-1024
	global_store_dwordx4 v[6:7], v[22:25], off
	v_lshl_add_u64 v[6:7], v[6:7], 0, s[4:5]
	v_lshl_add_u64 v[84:85], s[40:41], 0, v[4:5]
	global_load_dwordx4 v[60:63], v[84:85], off
	v_lshl_add_u64 v[86:87], s[40:41], 0, v[2:3]
	v_add_co_u32_e32 v86, vcc, 0x6600000, v86
	s_nop 1
	v_addc_co_u32_e32 v87, vcc, 0, v87, vcc
	global_load_dwordx2 v[64:65], v[86:87], off
	global_load_dwordx2 v[66:67], v[86:87], off offset:512
	global_load_dwordx2 v[68:69], v[86:87], off offset:1024
	global_load_dwordx2 v[70:71], v[86:87], off offset:1536
	v_lshl_add_u64 v[2:3], v[2:3], 0, s[0:1]
	v_lshl_add_u64 v[4:5], v[4:5], 0, s[2:3]
	s_waitcnt vmcnt(9)
	v_add_f32_e32 v42, v73, v72
	v_add_f32_e32 v43, v74, v75
	v_add_f32_e32 v42, v42, v43
	v_lshlrev_b32_e32 v26, 16, v76
	v_and_b32_e32 v27, 0xffff0000, v76
	v_add_f32_dpp v42, v42, v42 quad_perm:[1,0,3,2] row_mask:0xf bank_mask:0xf bound_ctrl:1
	v_lshlrev_b32_e32 v28, 16, v77
	v_and_b32_e32 v29, 0xffff0000, v77
	v_add_f32_dpp v42, v42, v42 quad_perm:[2,3,0,1] row_mask:0xf bank_mask:0xf bound_ctrl:1
	v_fmamk_f32 v42, v42, 0x3a800000, v9
	v_mul_f32_e32 v43, 0x4b800000, v42
	v_cmp_gt_f32_e32 vcc, s8, v42
	v_lshlrev_b32_e32 v30, 16, v78
	v_and_b32_e32 v31, 0xffff0000, v78
	v_cndmask_b32_e32 v42, v42, v43, vcc
	v_rsq_f32_e32 v42, v42
	v_lshlrev_b32_e32 v32, 16, v79
	v_and_b32_e32 v33, 0xffff0000, v79
	v_lshlrev_b32_e32 v34, 16, v80
	v_and_b32_e32 v35, 0xffff0000, v80
	v_mul_f32_e32 v43, 0x45800000, v42
	s_nop 0
	v_cndmask_b32_e32 v42, v42, v43, vcc
	v_lshlrev_b32_e32 v36, 16, v81
	v_and_b32_e32 v37, 0xffff0000, v81
	v_lshlrev_b32_e32 v38, 16, v82
	v_and_b32_e32 v39, 0xffff0000, v82
	v_lshlrev_b32_e32 v40, 16, v83
	v_and_b32_e32 v41, 0xffff0000, v83
	v_pk_mul_f32 v[26:27], v[42:43], v[26:27] op_sel_hi:[0,1]
	v_pk_mul_f32 v[28:29], v[42:43], v[28:29] op_sel_hi:[0,1]
	v_pk_mul_f32 v[30:31], v[42:43], v[30:31] op_sel_hi:[0,1]
	v_pk_mul_f32 v[32:33], v[42:43], v[32:33] op_sel_hi:[0,1]
	v_pk_mul_f32 v[34:35], v[42:43], v[34:35] op_sel_hi:[0,1]
	v_pk_mul_f32 v[36:37], v[42:43], v[36:37] op_sel_hi:[0,1]
	v_pk_mul_f32 v[38:39], v[42:43], v[38:39] op_sel_hi:[0,1]
	v_pk_mul_f32 v[40:41], v[42:43], v[40:41] op_sel_hi:[0,1]
	v_pk_mul_f32 v[10:11], v[44:45], v[26:27]
	v_pk_mul_f32 v[12:13], v[46:47], v[28:29]
	v_pk_mul_f32 v[14:15], v[48:49], v[30:31]
	v_pk_mul_f32 v[16:17], v[50:51], v[32:33]
	v_pk_mul_f32 v[18:19], v[52:53], v[34:35]
	v_pk_mul_f32 v[20:21], v[54:55], v[36:37]
	v_pk_mul_f32 v[22:23], v[56:57], v[38:39]
	v_pk_mul_f32 v[24:25], v[58:59], v[40:41]
	global_store_dwordx4 v[6:7], v[10:13], off offset:-3072
	global_store_dwordx4 v[6:7], v[14:17], off offset:-2048
	global_store_dwordx4 v[6:7], v[18:21], off offset:-1024
	global_store_dwordx4 v[6:7], v[22:25], off
	v_lshl_add_u64 v[6:7], v[6:7], 0, s[4:5]
	v_lshl_add_u64 v[84:85], s[40:41], 0, v[4:5]
	global_load_dwordx4 v[72:75], v[84:85], off
	v_lshl_add_u64 v[86:87], s[40:41], 0, v[2:3]
	v_add_co_u32_e32 v86, vcc, 0x6600000, v86
	s_nop 1
	v_addc_co_u32_e32 v87, vcc, 0, v87, vcc
	global_load_dwordx2 v[76:77], v[86:87], off
	global_load_dwordx2 v[78:79], v[86:87], off offset:512
	global_load_dwordx2 v[80:81], v[86:87], off offset:1024
	global_load_dwordx2 v[82:83], v[86:87], off offset:1536
	v_lshl_add_u64 v[2:3], v[2:3], 0, s[0:1]
	v_lshl_add_u64 v[4:5], v[4:5], 0, s[2:3]
	s_waitcnt vmcnt(9)
	v_add_f32_e32 v42, v61, v60
	v_add_f32_e32 v43, v62, v63
	v_add_f32_e32 v42, v42, v43
	v_lshlrev_b32_e32 v26, 16, v64
	v_and_b32_e32 v27, 0xffff0000, v64
	v_add_f32_dpp v42, v42, v42 quad_perm:[1,0,3,2] row_mask:0xf bank_mask:0xf bound_ctrl:1
	v_lshlrev_b32_e32 v28, 16, v65
	v_and_b32_e32 v29, 0xffff0000, v65
	v_add_f32_dpp v42, v42, v42 quad_perm:[2,3,0,1] row_mask:0xf bank_mask:0xf bound_ctrl:1
	v_fmamk_f32 v42, v42, 0x3a800000, v9
	v_mul_f32_e32 v43, 0x4b800000, v42
	v_cmp_gt_f32_e32 vcc, s8, v42
	v_lshlrev_b32_e32 v30, 16, v66
	v_and_b32_e32 v31, 0xffff0000, v66
	v_cndmask_b32_e32 v42, v42, v43, vcc
	v_rsq_f32_e32 v42, v42
	v_lshlrev_b32_e32 v32, 16, v67
	v_and_b32_e32 v33, 0xffff0000, v67
	v_lshlrev_b32_e32 v34, 16, v68
	v_and_b32_e32 v35, 0xffff0000, v68
	v_mul_f32_e32 v43, 0x45800000, v42
	s_nop 0
	v_cndmask_b32_e32 v42, v42, v43, vcc
	v_lshlrev_b32_e32 v36, 16, v69
	v_and_b32_e32 v37, 0xffff0000, v69
	v_lshlrev_b32_e32 v38, 16, v70
	v_and_b32_e32 v39, 0xffff0000, v70
	v_lshlrev_b32_e32 v40, 16, v71
	v_and_b32_e32 v41, 0xffff0000, v71
	v_pk_mul_f32 v[26:27], v[42:43], v[26:27] op_sel_hi:[0,1]
	v_pk_mul_f32 v[28:29], v[42:43], v[28:29] op_sel_hi:[0,1]
	v_pk_mul_f32 v[30:31], v[42:43], v[30:31] op_sel_hi:[0,1]
	v_pk_mul_f32 v[32:33], v[42:43], v[32:33] op_sel_hi:[0,1]
	v_pk_mul_f32 v[34:35], v[42:43], v[34:35] op_sel_hi:[0,1]
	v_pk_mul_f32 v[36:37], v[42:43], v[36:37] op_sel_hi:[0,1]
	v_pk_mul_f32 v[38:39], v[42:43], v[38:39] op_sel_hi:[0,1]
	v_pk_mul_f32 v[40:41], v[42:43], v[40:41] op_sel_hi:[0,1]
	v_pk_mul_f32 v[10:11], v[44:45], v[26:27]
	v_pk_mul_f32 v[12:13], v[46:47], v[28:29]
	v_pk_mul_f32 v[14:15], v[48:49], v[30:31]
	v_pk_mul_f32 v[16:17], v[50:51], v[32:33]
	v_pk_mul_f32 v[18:19], v[52:53], v[34:35]
	v_pk_mul_f32 v[20:21], v[54:55], v[36:37]
	v_pk_mul_f32 v[22:23], v[56:57], v[38:39]
	v_pk_mul_f32 v[24:25], v[58:59], v[40:41]
	global_store_dwordx4 v[6:7], v[10:13], off offset:-3072
	global_store_dwordx4 v[6:7], v[14:17], off offset:-2048
	global_store_dwordx4 v[6:7], v[18:21], off offset:-1024
	global_store_dwordx4 v[6:7], v[22:25], off
	v_lshl_add_u64 v[6:7], v[6:7], 0, s[4:5]
	s_waitcnt vmcnt(4)
	v_add_f32_e32 v42, v73, v72
	v_add_f32_e32 v43, v74, v75
	v_add_f32_e32 v42, v42, v43
	v_lshlrev_b32_e32 v26, 16, v76
	v_and_b32_e32 v27, 0xffff0000, v76
	v_add_f32_dpp v42, v42, v42 quad_perm:[1,0,3,2] row_mask:0xf bank_mask:0xf bound_ctrl:1
	v_lshlrev_b32_e32 v28, 16, v77
	v_and_b32_e32 v29, 0xffff0000, v77
	v_add_f32_dpp v42, v42, v42 quad_perm:[2,3,0,1] row_mask:0xf bank_mask:0xf bound_ctrl:1
	v_fmamk_f32 v42, v42, 0x3a800000, v9
	v_mul_f32_e32 v43, 0x4b800000, v42
	v_cmp_gt_f32_e32 vcc, s8, v42
	v_lshlrev_b32_e32 v30, 16, v78
	v_and_b32_e32 v31, 0xffff0000, v78
	v_cndmask_b32_e32 v42, v42, v43, vcc
	v_rsq_f32_e32 v42, v42
	v_lshlrev_b32_e32 v32, 16, v79
	v_and_b32_e32 v33, 0xffff0000, v79
	v_lshlrev_b32_e32 v34, 16, v80
	v_and_b32_e32 v35, 0xffff0000, v80
	v_mul_f32_e32 v43, 0x45800000, v42
	s_nop 0
	v_cndmask_b32_e32 v42, v42, v43, vcc
	v_lshlrev_b32_e32 v36, 16, v81
	v_and_b32_e32 v37, 0xffff0000, v81
	v_lshlrev_b32_e32 v38, 16, v82
	v_and_b32_e32 v39, 0xffff0000, v82
	v_lshlrev_b32_e32 v40, 16, v83
	v_and_b32_e32 v41, 0xffff0000, v83
	v_pk_mul_f32 v[26:27], v[42:43], v[26:27] op_sel_hi:[0,1]
	v_pk_mul_f32 v[28:29], v[42:43], v[28:29] op_sel_hi:[0,1]
	v_pk_mul_f32 v[30:31], v[42:43], v[30:31] op_sel_hi:[0,1]
	v_pk_mul_f32 v[32:33], v[42:43], v[32:33] op_sel_hi:[0,1]
	v_pk_mul_f32 v[34:35], v[42:43], v[34:35] op_sel_hi:[0,1]
	v_pk_mul_f32 v[36:37], v[42:43], v[36:37] op_sel_hi:[0,1]
	v_pk_mul_f32 v[38:39], v[42:43], v[38:39] op_sel_hi:[0,1]
	v_pk_mul_f32 v[40:41], v[42:43], v[40:41] op_sel_hi:[0,1]
	v_pk_mul_f32 v[10:11], v[44:45], v[26:27]
	v_pk_mul_f32 v[12:13], v[46:47], v[28:29]
	v_pk_mul_f32 v[14:15], v[48:49], v[30:31]
	v_pk_mul_f32 v[16:17], v[50:51], v[32:33]
	v_pk_mul_f32 v[18:19], v[52:53], v[34:35]
	v_pk_mul_f32 v[20:21], v[54:55], v[36:37]
	v_pk_mul_f32 v[22:23], v[56:57], v[38:39]
	v_pk_mul_f32 v[24:25], v[58:59], v[40:41]
	global_store_dwordx4 v[6:7], v[10:13], off offset:-3072
	global_store_dwordx4 v[6:7], v[14:17], off offset:-2048
	global_store_dwordx4 v[6:7], v[18:21], off offset:-1024
	global_store_dwordx4 v[6:7], v[22:25], off
	v_lshl_add_u64 v[6:7], v[6:7], 0, s[4:5]
